# scan prologue: the per-head table loads no longer complete before the first chunk's 20 operand loads are issued (one global round trip instead of two per workgroup)
# baseline (speedup 1.0000x reference)
; __device__ __forceinline__ void phase_scan(const Params& p, LAS unsigned char* lds) {
;     ...
;         __syncthreads();
;         for (int i = tid; i < 4096; i += 512) { const int l = i >> 6, c = i & 63; w2T[c * 72 + l] = (h16)w2[l * 1024 + c]; a2T[c * 72 + l] = (h16)a2[l * 1024 + c]; }
;         const int pw_ = wave & 3, s_sub = lane >> 3, c8 = (lane & 7) * 8, s_l = 8 * pw_ + s_sub;
;         h16x8 mu_r8, mu_k8, mu_v8, mu_w8, mu_a8; f32x2 w0r[4], a0r[4], kkr[4], kar[4], omk[4], rkr[4];
; #pragma unroll
;         for (int e = 0; e < 8; ++e) { mu_r8[e] = (h16)mu[64 * h + c8 + e]; mu_k8[e] = (h16)mu[1024 + 64 * h + c8 + e]; mu_v8[e] = (h16)mu[2048 + 64 * h + c8 + e]; mu_w8[e] = (h16)mu[3072 + c8 + e]; mu_a8[e] = (h16)mu[3136 + c8 + e];
;             w0r[e >> 1][e & 1] = w0[c8 + e]; a0r[e >> 1][e & 1] = a0[c8 + e]; kkr[e >> 1][e & 1] = kkw[c8 + e]; kar[e >> 1][e & 1] = kaw[c8 + e]; omk[e >> 1][e & 1] = 1.f - kaw[c8 + e]; rkr[e >> 1][e & 1] = rkw[c8 + e]; }
;         f32x2 S01 = {0.f, 0.f}, S23 = {0.f, 0.f};
;         const int srow = 4 * (wave & 3) + (lane >> 4), j0 = 4 * (lane & 15);
;         const h16x8 z8 = {0, 0, 0, 0, 0, 0, 0, 0};
;         h16x8 pr, pk, pv, pw, pa, qr_, qk_, qv_, qw_, qa_;
;         const h16 *pcA, *pcB, *ppA, *ppB;
;         { const int t0_ = dir ? (SEQ - 1 - s_l) : s_l; pcA = PC + (size_t)(b * SEQ + t0_) * 3200 + c8 + 64 * h; pcB = pcA + 2048 - 64 * h;
;           const long po_ = (s_l > 0) ? (dir ? 3200 : -3200) : 0; ppA = pcA + po_; ppB = pcB + po_; }
;         const long cstride_ = dir ? -32 * 3200 : 32 * 3200;
;     ...
;         if (wave >= 4) { SCAN_LOAD_RAW(); if (s_l == 0) { qr_ = z8; qk_ = z8; qv_ = z8; qw_ = z8; qa_ = z8; } }
.LBB0_595:
	s_lshl_b32 s8, s78, 3
	s_and_b32 s46, s8, 56
	s_ashr_i32 s8, s78, 5
	s_add_i32 s46, s46, s8
	s_ashr_i32 s12, s46, 5
	s_and_b32 s14, s46, 15
	s_ashr_i32 s13, s12, 31
	s_lshl_b32 s15, s14, 6
	s_lshl_b64 s[10:11], s[12:13], 18
	s_add_u32 s8, s62, s10
	s_addc_u32 s9, s63, s11
	s_lshl_b32 s20, s14, 8
	s_add_u32 s8, s8, s20
	s_addc_u32 s9, s9, 0
	s_add_u32 s10, s66, s10
	s_addc_u32 s11, s67, s11
	s_add_u32 s10, s10, s20
	s_waitcnt vmcnt(0)
	s_barrier
	s_addc_u32 s11, s11, 0
	s_and_saveexec_b64 s[40:41], s[6:7]
	global_load_dword v240, v199, s[8:9]
	global_load_dword v241, v199, s[10:11]
	s_or_b64 exec, exec, s[40:41]
	global_load_dword v226, v192, s[8:9]
	global_load_dword v227, v193, s[8:9]
	global_load_dword v228, v194, s[8:9]
	global_load_dword v229, v195, s[8:9]
	global_load_dword v230, v196, s[8:9]
	global_load_dword v231, v197, s[8:9]
	global_load_dword v232, v198, s[8:9]
	global_load_dword v233, v192, s[10:11]
	global_load_dword v234, v193, s[10:11]
	global_load_dword v235, v194, s[10:11]
	global_load_dword v236, v195, s[10:11]
	global_load_dword v237, v196, s[10:11]
	global_load_dword v238, v197, s[10:11]
	global_load_dword v239, v198, s[10:11]
	s_lshl_b32 s10, s12, 10
	s_mul_i32 s8, s12, 0xc80
	s_ashr_i32 s11, s10, 31
	s_ashr_i32 s9, s8, 31
	s_lshl_b64 s[10:11], s[10:11], 2
	s_add_u32 s40, s64, s10
	s_addc_u32 s41, s65, s11
	s_lshl_b64 s[8:9], s[8:9], 2
	s_add_u32 s34, s58, s8
	s_addc_u32 s35, s59, s9
	s_add_u32 s8, s60, s10
	v_or_b32_e32 v0, s15, v132
	s_addc_u32 s9, s61, s11
	s_lshl_b32 s20, s15, 2
	v_lshlrev_b32_e32 v0, 2, v0
	s_add_u32 s10, s8, s20
	v_lshl_add_u64 v[2:3], s[34:35], 0, v[0:1]
	s_addc_u32 s11, s9, 0
	v_add_co_u32_e64 v22, s[8:9], s37, v2
	v_lshl_add_u64 v[20:21], v[2:3], 0, s[22:23]
	s_nop 0
	v_addc_co_u32_e64 v23, s[8:9], 0, v3, s[8:9]
	v_lshl_add_u64 v[2:3], v[2:3], 0, s[24:25]
	v_lshlrev_b32_e32 v144, 2, v132
	v_mov_b32_e32 v145, v1
	global_load_dwordx4 v[74:77], v0, s[34:35] offset:16
	global_load_dwordx4 v[60:63], v0, s[34:35]
	global_load_dwordx4 v[90:93], v[22:23], off offset:-4096
	global_load_dwordx4 v[64:67], v[22:23], off
	global_load_dwordx4 v[82:85], v[20:21], off offset:16
	global_load_dwordx4 v[70:73], v[2:3], off offset:16
	v_lshl_add_u64 v[2:3], s[34:35], 0, v[144:145]
	v_add_co_u32_e64 v22, s[8:9], s39, v2
	s_add_u32 s40, s40, s20
	v_lshl_add_u64 v[20:21], v[2:3], 0, s[26:27]
	v_addc_co_u32_e64 v23, s[8:9], 0, v3, s[8:9]
	v_lshl_add_u64 v[2:3], v[2:3], 0, s[28:29]
	v_lshl_add_u64 v[48:49], v[138:139], 0, s[20:21]
	v_lshl_add_u64 v[56:57], v[140:141], 0, s[20:21]
	s_addc_u32 s41, s41, 0
	global_load_dwordx4 v[94:97], v[22:23], off
	global_load_dwordx4 v[86:89], v[20:21], off offset:16
	global_load_dwordx4 v[98:101], v[22:23], off offset:256
	global_load_dwordx4 v[78:81], v[2:3], off offset:16
	v_lshl_add_u64 v[2:3], v[136:137], 0, s[20:21]
	global_load_dwordx4 v[20:23], v144, s[10:11] offset:16
	global_load_dwordx4 v[24:27], v144, s[10:11]
	global_load_dwordx4 v[28:31], v144, s[40:41] offset:16
	global_load_dwordx4 v[32:35], v144, s[40:41]
	global_load_dwordx4 v[36:39], v[2:3], off offset:16
	global_load_dwordx4 v[40:43], v[2:3], off
	global_load_dwordx4 v[44:47], v[48:49], off offset:16
	s_nop 0
	global_load_dwordx4 v[48:51], v[48:49], off
	s_nop 0
	global_load_dwordx4 v[52:55], v[56:57], off offset:16
	s_nop 0
	global_load_dwordx4 v[56:59], v[56:57], off
	s_waitcnt vmcnt(33)
	v_cvt_f16_f32_e32 v226, v226
	s_waitcnt vmcnt(32)
	v_cvt_f16_f32_e32 v227, v227
	s_waitcnt vmcnt(31)
	v_cvt_f16_f32_e32 v228, v228
	s_waitcnt vmcnt(30)
	v_cvt_f16_f32_e32 v229, v229
	ds_write_b16 v185, v226
	s_waitcnt vmcnt(26)
	v_cvt_f16_f32_e32 v226, v233
	s_waitcnt vmcnt(25)
	v_cvt_f16_f32_e32 v233, v234
	v_cvt_f16_f32_e32 v230, v230
	v_cvt_f16_f32_e32 v231, v231
	v_cvt_f16_f32_e32 v232, v232
	s_waitcnt vmcnt(24)
	v_cvt_f16_f32_e32 v234, v235
	s_waitcnt vmcnt(23)
	v_cvt_f16_f32_e32 v235, v236
	s_waitcnt vmcnt(22)
	v_cvt_f16_f32_e32 v236, v237
	s_waitcnt vmcnt(21)
	v_cvt_f16_f32_e32 v237, v238
	s_waitcnt vmcnt(20)
	v_cvt_f16_f32_e32 v238, v239
	ds_write_b16 v185, v226 offset:9216
	ds_write_b16 v186, v227
	ds_write_b16 v186, v233 offset:9216
	ds_write_b16 v185, v228 offset:32
	ds_write_b16 v185, v234 offset:9248
	ds_write_b16 v187, v229
	ds_write_b16 v187, v235 offset:9216
	ds_write_b16 v185, v230 offset:64
	ds_write_b16 v185, v236 offset:9280
	ds_write_b16 v188, v231
	ds_write_b16 v188, v237 offset:9216
	ds_write_b16 v189, v232
	ds_write_b16 v189, v238 offset:9216
	s_and_saveexec_b64 s[48:49], s[6:7]
	s_waitcnt vmcnt(35)
	v_cvt_f16_f32_e32 v240, v240
	s_waitcnt vmcnt(34)
	v_cvt_f16_f32_e32 v241, v241
	ds_write_b16 v190, v240
	ds_write_b16 v190, v241 offset:9216
	s_or_b64 exec, exec, s[48:49]
	s_cmp_lt_u32 s46, 32
	s_cselect_b64 s[8:9], -1, 0
	s_lshl_b32 s10, s46, 9
	v_cndmask_b32_e64 v0, v170, v169, s[8:9]
	s_and_b32 s79, s10, 0x2000
	v_or_b32_e32 v0, s79, v0
	v_mul_u32_u24_e32 v0, 0xc80, v0
	v_lshlrev_b32_e32 v0, 1, v0
	v_lshl_add_u64 v[2:3], v[134:135], 0, v[0:1]
	s_lshl_b32 s20, s15, 1
	v_lshl_add_u64 v[146:147], v[2:3], 0, s[20:21]
	v_lshl_add_u64 v[2:3], v[146:147], 0, s[22:23]
	v_subrev_co_u32_e64 v148, s[10:11], s20, v2
	s_nop 1
	v_subbrev_co_u32_e64 v149, s[10:11], 0, v3, s[10:11]
	s_and_b64 s[10:11], s[8:9], exec
	s_cselect_b32 s41, -1, 0
	s_cselect_b32 s40, s76, 0xc80
	v_mov_b32_e32 v0, s41
	v_cndmask_b32_e64 v69, v0, 0, vcc
	v_mov_b32_e32 v0, s40
	v_cndmask_b32_e64 v68, v0, 0, vcc
	v_lshlrev_b64 v[68:69], 1, v[68:69]
	v_lshl_add_u64 v[152:153], v[146:147], 0, v[68:69]
	v_lshl_add_u64 v[150:151], v[148:149], 0, v[68:69]
	s_cselect_b32 s47, 0, -1
	s_cselect_b32 s46, s77, 0xfffe7000
	s_and_saveexec_b64 s[10:11], s[0:1]
	s_cbranch_execz .LBB0_601
	global_load_dwordx4 v[102:105], v[146:147], off
	global_load_dwordx4 v[106:109], v[146:147], off offset:2048
	global_load_dwordx4 v[4:7], v[148:149], off offset:2048
	global_load_dwordx4 v[8:11], v[148:149], off offset:2176
	global_load_dwordx4 v[114:117], v[152:153], off
	global_load_dwordx4 v[118:121], v[152:153], off offset:2048
	v_lshl_add_u64 v[12:13], v[150:151], 0, s[20:21]
	global_load_dwordx4 v[110:113], v[2:3], off
	global_load_dwordx4 v[122:125], v[12:13], off
	s_nop 0
	global_load_dwordx4 v[12:15], v[150:151], off offset:2048
	global_load_dwordx4 v[16:19], v[150:151], off offset:2176
	s_and_saveexec_b64 s[48:49], vcc
	s_cbranch_execz .LBB0_600
	v_mov_b32_e32 v2, v1
	v_mov_b32_e32 v3, v1
	v_mov_b32_e32 v0, v1
	s_waitcnt vmcnt(5)
	v_mov_b64_e32 v[116:117], v[2:3]
	s_waitcnt vmcnt(4)
	v_mov_b64_e32 v[120:121], v[2:3]
	s_waitcnt vmcnt(2)
	v_mov_b64_e32 v[124:125], v[2:3]
	s_waitcnt vmcnt(1)
	v_mov_b64_e32 v[14:15], v[2:3]
	s_waitcnt vmcnt(0)
	v_mov_b64_e32 v[18:19], v[2:3]
	v_mov_b64_e32 v[114:115], v[0:1]
	v_mov_b64_e32 v[118:119], v[0:1]
	v_mov_b64_e32 v[122:123], v[0:1]
	v_mov_b64_e32 v[12:13], v[0:1]
	v_mov_b64_e32 v[16:17], v[0:1]
